# prep phase: modulation-row loads issued together with the x loads (one L2 round trip less per iteration)
# baseline (speedup 1.0000x reference)
.LBB0_158:
	s_or_b64 exec, exec, s[6:7]
	global_load_dwordx4 v[14:17], v[12:13], off
	global_load_dwordx4 v[18:21], v[12:13], off offset:16
	v_lshlrev_b64 v[30:31], 1, v[10:11]
	v_add_u32_e32 v10, 0xffffe000, v8
	v_lshlrev_b32_e32 v4, 1, v6
	v_lshl_add_u64 v[8:9], s[12:13], 0, v[30:31]
	v_lshrrev_b32_e32 v12, 12, v10
	v_lshl_add_u64 v[10:11], v[8:9], 0, v[4:5]
	v_add_u32_e32 v8, 1, v12
	v_mul_hi_u32_u24_e32 v9, 0x6000, v8
	v_mul_u32_u24_e32 v8, 0x6000, v8
	v_cndmask_b32_e64 v9, v9, 0, vcc
	v_cndmask_b32_e64 v8, v8, 0, vcc
	v_lshlrev_b32_e32 v6, 2, v6
	v_mov_b32_e32 v7, v5
	v_lshl_add_u64 v[8:9], s[4:5], 0, v[8:9]
	v_lshl_add_u64 v[32:33], v[8:9], 0, v[6:7]
	v_add_co_u32_e32 v12, vcc, s30, v32
	v_lshl_add_u64 v[34:35], v[32:33], 0, s[26:27]
	s_nop 0
	v_addc_co_u32_e32 v13, vcc, 0, v33, vcc
	v_lshl_add_u64 v[2:3], v[2:3], 0, s[16:17]
	v_lshl_add_u64 v[30:31], s[14:15], 0, v[30:31]
	v_cmp_lt_u64_e32 vcc, s[28:29], v[2:3]
	v_lshl_add_u64 v[30:31], v[30:31], 0, v[4:5]
	s_or_b64 s[18:19], vcc, s[18:19]
	v_add_u32_e32 v1, s1, v1
	global_load_dwordx4 v[40:43], v[12:13], off
	global_load_dwordx4 v[44:47], v[34:35], off offset:16
	global_load_dwordx4 v[48:51], v[32:33], off
	global_load_dwordx4 v[52:55], v[32:33], off offset:16
	s_waitcnt vmcnt(5)
	v_cvt_pk_bf16_f32 v6, v14, v15
	v_cvt_pk_bf16_f32 v7, v16, v17
	s_waitcnt vmcnt(4)
	v_cvt_pk_bf16_f32 v8, v18, v19
	v_cvt_pk_bf16_f32 v9, v20, v21
	global_store_dwordx4 v[10:11], v[6:9], off
	s_nop 0
	s_waitcnt vmcnt(4)
	v_pk_add_f32 v[6:7], v[40:41], 1.0 op_sel_hi:[1,0]
	v_pk_add_f32 v[8:9], v[42:43], 1.0 op_sel_hi:[1,0]
	s_waitcnt vmcnt(3)
	v_pk_add_f32 v[10:11], v[44:45], 1.0 op_sel_hi:[1,0]
	v_pk_add_f32 v[12:13], v[46:47], 1.0 op_sel_hi:[1,0]
	s_waitcnt vmcnt(2)
	v_pk_fma_f32 v[6:7], v[14:15], v[6:7], v[48:49]
	v_pk_fma_f32 v[8:9], v[16:17], v[8:9], v[50:51]
	s_waitcnt vmcnt(1)
	v_pk_fma_f32 v[10:11], v[18:19], v[10:11], v[52:53]
	v_pk_fma_f32 v[12:13], v[20:21], v[12:13], v[54:55]
	v_cvt_pk_bf16_f32 v6, v6, v7
	v_cvt_pk_bf16_f32 v7, v8, v9
	v_cvt_pk_bf16_f32 v8, v10, v11
	v_cvt_pk_bf16_f32 v9, v12, v13
	global_store_dwordx4 v[30:31], v[6:9], off
	s_andn2_b64 exec, exec, s[18:19]
	s_cbranch_execz .LBB0_163
